# plus: attention ck prefetch no longer stalls wave 0; gMLP gating group loop hand-written (loads one group ahead); cumsum loads batched
# baseline (speedup 1.0000x reference)
; #define LAS __attribute__((address_space(3)))
; __device__ __forceinline__ void gate_prompt_unit(ArgsK& a, LAS unsigned char* lds, int n, int tid, int wave, int lane) {
;     ...
;     const int sch = tid & 31, srb = tid >> 5;
;     const int t = wave * 16 + l15, nch = (wave < 4) ? 2 : 4;
;     f32x4 xr[8];
; #pragma unroll
;     for (int i = 0; i < 8; ++i) xr[i] = ({ const u32x2 w_ = *(const u32x2*)(VR + (r0 + srb + 16 * i) * DM + sch * 4); (f32x4){bf2f(w_.x & 0xffff), bf2f(w_.x >> 16), bf2f(w_.y & 0xffff), bf2f(w_.y >> 16)}; });
;     for (int g = 0; g < 8; ++g) {
;         { const f32x4 lg = *(const f32x4*)(a.in[25] + g * 128 + sch * 4), lb = *(const f32x4*)(a.in[26] + g * 128 + sch * 4);
; #pragma unroll
;           for (int i = 0; i < 8; ++i) { const int row = srb + 16 * i; const float mean = ST[row * 2], rstd = ST[row * 2 + 1];
;               const f32x4 x = (xr[i] - mean) * rstd * lg + lb; u32x2 w; w.x = cvt_pk_bf16(x[0], x[1]); w.y = cvt_pk_bf16(x[2], x[3]);
;               *(LAS u32x2*)(lds + GT_V + row * GT_VSTR + sch * 8) = w; } }
;         __syncthreads();
;         if (g + 1 < 8) {
; #pragma unroll
;             for (int i = 0; i < 8; ++i) xr[i] = ({ const u32x2 w_ = __builtin_nontemporal_load((const u32x2*)(VR + (r0 + srb + 16 * i) * DM + (g + 1) * 128 + sch * 4)); (f32x4){bf2f(w_.x & 0xffff), bf2f(w_.x >> 16), bf2f(w_.y & 0xffff), bf2f(w_.y >> 16)}; }); }
;         u32x2 uw[8];
; #pragma unroll
;         for (int cb = 0; cb < 8; ++cb) uw[cb] = __builtin_nontemporal_load((const u32x2*)(U + (r0 + t) * DM + g * 128 + cb * 16 + quad * 4));
;         f32x4 acc[8];
; #pragma unroll
;         for (int cb = 0; cb < 8; ++cb) acc[cb] = (f32x4){0.f, 0.f, 0.f, 0.f};
;         for (int c = 0; c < nch; ++c) { const bf16_t* wp = WSM + ((size_t)(g * 128 + t)) * 128 + 32 * c + quad * 4;
;             const u32x2 w1 = *(const u32x2*)wp, w2 = *(const u32x2*)(wp + 16); const bf16x8 wf = __builtin_bit_cast(bf16x8, ((u32x4){w1.x, w1.y, w2.x, w2.y}));
; #pragma unroll
;             for (int cb = 0; cb < 8; ++cb) { LAS unsigned char* vp = lds + GT_V + (32 * c + quad * 4 + (l15 >> 2)) * GT_VSTR + cb * 32 + (lane & 3) * 8;
;                 const s16x4 r1 = tr_read(vp), r2 = tr_read(vp + 16 * GT_VSTR);
;                 acc[cb] = MFMA16(((bf16x8){r1[0], r1[1], r1[2], r1[3], r2[0], r2[1], r2[2], r2[3]}), wf, acc[cb]); } }
;         const float bias = a.in[28][g * 128 + t];
.LBB0_141:
	s_or_b64 exec, exec, s[6:7]
	s_load_dwordx2 s[6:7], s[38:39], 0xe0
	v_add_u32_e32 v137, 0xffffed20, v69
	v_lshl_add_u64 v[2:3], s[4:5], 0, v[70:71]
	v_lshlrev_b64 v[2:3], 11, v[2:3]
	v_lshl_add_u64 v[86:87], v[72:73], 0, v[2:3]
	s_mov_b32 s3, 0x8000
	v_add_co_u32_e32 v2, vcc, s3, v86
	s_mov_b32 s3, 0x10000
	s_nop 0
	v_addc_co_u32_e32 v3, vcc, 0, v87, vcc
	v_add_co_u32_e32 v4, vcc, s3, v86
	s_mov_b32 s3, 0x18000
	s_nop 0
	v_addc_co_u32_e32 v5, vcc, 0, v87, vcc
	v_add_co_u32_e32 v8, vcc, s3, v86
	s_mov_b32 s3, 0x20000
	s_nop 0
	v_addc_co_u32_e32 v9, vcc, 0, v87, vcc
	s_waitcnt lgkmcnt(0)
	s_barrier
	global_load_dwordx2 v[6:7], v[86:87], off
	global_load_dwordx2 v[10:11], v[2:3], off
	global_load_dwordx2 v[14:15], v[4:5], off
	global_load_dwordx2 v[18:19], v[8:9], off
	v_add_co_u32_e32 v2, vcc, s3, v86
	s_mov_b32 s3, 0x28000
	s_nop 0
	v_addc_co_u32_e32 v3, vcc, 0, v87, vcc
	v_add_co_u32_e32 v4, vcc, s3, v86
	s_mov_b32 s3, 0x30000
	s_nop 0
	v_addc_co_u32_e32 v5, vcc, 0, v87, vcc
	global_load_dwordx2 v[22:23], v[2:3], off
	global_load_dwordx2 v[26:27], v[4:5], off
	v_add_co_u32_e32 v2, vcc, s3, v86
	s_mov_b32 s3, 0x38000
	s_nop 0
	v_addc_co_u32_e32 v3, vcc, 0, v87, vcc
	global_load_dwordx2 v[30:31], v[2:3], off
	v_add_co_u32_e32 v2, vcc, s3, v86
	s_mov_b32 s3, 0
	s_nop 0
	v_addc_co_u32_e32 v3, vcc, 0, v87, vcc
	global_load_dwordx2 v[34:35], v[2:3], off
	v_lshl_add_u64 v[2:3], s[4:5], 0, v[74:75]
	v_lshlrev_b64 v[36:37], 11, v[2:3]
	v_lshl_add_u64 v[88:89], v[80:81], 0, v[36:37]
	v_lshl_add_u64 v[90:91], v[84:85], 0, v[36:37]
	s_waitcnt vmcnt(6)
	v_and_b32_e32 v9, 0xffff0000, v10
	v_and_b32_e32 v3, 0xffff0000, v7
	v_and_b32_e32 v5, 0xffff0000, v6
	v_lshlrev_b32_e32 v0, 16, v6
	v_lshlrev_b32_e32 v2, 16, v7
	v_and_b32_e32 v7, 0xffff0000, v11
	v_lshlrev_b32_e32 v4, 16, v10
	v_lshlrev_b32_e32 v6, 16, v11
	s_waitcnt vmcnt(5)
	v_and_b32_e32 v11, 0xffff0000, v15
	v_and_b32_e32 v13, 0xffff0000, v14
	v_lshlrev_b32_e32 v8, 16, v14
	v_lshlrev_b32_e32 v10, 16, v15
	s_waitcnt vmcnt(4)
	v_and_b32_e32 v15, 0xffff0000, v19
	v_and_b32_e32 v17, 0xffff0000, v18
	v_lshlrev_b32_e32 v12, 16, v18
	v_lshlrev_b32_e32 v14, 16, v19
	s_waitcnt vmcnt(3)
	v_and_b32_e32 v19, 0xffff0000, v23
	v_and_b32_e32 v21, 0xffff0000, v22
	v_lshlrev_b32_e32 v16, 16, v22
	v_lshlrev_b32_e32 v18, 16, v23
	s_waitcnt vmcnt(2)
	v_and_b32_e32 v23, 0xffff0000, v27
	v_and_b32_e32 v25, 0xffff0000, v26
	v_lshlrev_b32_e32 v20, 16, v26
	v_lshlrev_b32_e32 v22, 16, v27
	s_waitcnt vmcnt(1)
	v_and_b32_e32 v27, 0xffff0000, v31
	v_and_b32_e32 v29, 0xffff0000, v30
	v_lshlrev_b32_e32 v24, 16, v30
	v_lshlrev_b32_e32 v26, 16, v31
	s_waitcnt vmcnt(0)
	v_and_b32_e32 v31, 0xffff0000, v35
	v_and_b32_e32 v33, 0xffff0000, v34
	v_lshlrev_b32_e32 v28, 16, v34
	v_lshlrev_b32_e32 v30, 16, v35
	s_mov_b32 s12, 0
	s_lshl_b32 s4, s12, 7
	v_add_u32_e32 v108, s4, v74
	v_ashrrev_i32_e32 v109, 31, v108
	v_lshlrev_b64 v[138:139], 8, v[108:109]
	v_lshl_add_u64 v[110:111], v[82:83], 0, v[138:139]
	global_load_dwordx2 v[230:231], v[110:111], off
	global_load_dwordx2 v[232:233], v[110:111], off offset:32
	global_load_dwordx2 v[234:235], v[110:111], off offset:64
	global_load_dwordx2 v[236:237], v[110:111], off offset:96
	global_load_dwordx2 v[238:239], v[110:111], off offset:128
	global_load_dwordx2 v[240:241], v[110:111], off offset:160
	global_load_dwordx2 v[242:243], v[110:111], off offset:192
	global_load_dwordx2 v[244:245], v[110:111], off offset:224
	v_lshl_add_u64 v[108:109], v[108:109], 2, s[6:7]
	global_load_dword v246, v[108:109], off
	s_mov_b32 s5, 0
	s_lshl_b32 s4, s12, 9
	v_lshl_add_u64 v[138:139], v[76:77], 0, s[4:5]
	global_load_dwordx4 v[222:225], v[138:139], off
	v_lshl_add_u64 v[138:139], v[78:79], 0, s[4:5]
	global_load_dwordx4 v[226:229], v[138:139], off
	s_lshl_b32 s4, s12, 8
	v_lshl_add_u64 v[138:139], v[88:89], 0, s[4:5]
	global_load_dwordx2 v[106:107], v[138:139], off nt
	global_load_dwordx2 v[104:105], v[138:139], off offset:32 nt
	global_load_dwordx2 v[102:103], v[138:139], off offset:64 nt
	global_load_dwordx2 v[100:101], v[138:139], off offset:96 nt
	global_load_dwordx2 v[98:99], v[138:139], off offset:128 nt
	global_load_dwordx2 v[96:97], v[138:139], off offset:160 nt
	global_load_dwordx2 v[94:95], v[138:139], off offset:192 nt
	global_load_dwordx2 v[92:93], v[138:139], off offset:224 nt
; __device__ __forceinline__ unsigned cvt_pk_bf16(float lo, float hi) { unsigned r; asm volatile("v_cvt_pk_bf16_f32 %0, %1, %2" : "=v"(r) : "v"(lo), "v"(hi)); return r; }
; #define LAS __attribute__((address_space(3)))
; __device__ __forceinline__ void gate_prompt_unit(ArgsK& a, LAS unsigned char* lds, int n, int tid, int wave, int lane) {
;     ...
;     for (int g = 0; g < 8; ++g) {
;         { const f32x4 lg = *(const f32x4*)(a.in[25] + g * 128 + sch * 4), lb = *(const f32x4*)(a.in[26] + g * 128 + sch * 4);
; #pragma unroll
;           for (int i = 0; i < 8; ++i) { const int row = srb + 16 * i; const float mean = ST[row * 2], rstd = ST[row * 2 + 1];
;               const f32x4 x = (xr[i] - mean) * rstd * lg + lb; u32x2 w; w.x = cvt_pk_bf16(x[0], x[1]); w.y = cvt_pk_bf16(x[2], x[3]);
;               *(LAS u32x2*)(lds + GT_V + row * GT_VSTR + sch * 8) = w; } }
.LBB0_142:
	s_lshl_b32 s12, s3, 7
	ds_read_b64 v[162:163], v67
	ds_read_b64 v[164:165], v117
	ds_read_b64 v[166:167], v118
	ds_read_b64 v[168:169], v119
	ds_read_b64 v[170:171], v120
	ds_read_b64 v[172:173], v121
	ds_read_b64 v[174:175], v122
	ds_read_b64 v[176:177], v123
	s_add_i32 s3, s3, 1
	s_waitcnt vmcnt(8)
	s_waitcnt lgkmcnt(7)
	v_sub_f32_e32 v180, v0, v162
	v_sub_f32_e32 v181, v5, v162
	v_sub_f32_e32 v182, v2, v162
	v_sub_f32_e32 v183, v3, v162
	v_pk_mul_f32 v[180:181], v[180:181], v[162:163] op_sel:[0,1]
	v_pk_mul_f32 v[182:183], v[182:183], v[162:163] op_sel:[0,1]
	v_pk_fma_f32 v[180:181], v[222:223], v[180:181], v[226:227]
	v_pk_fma_f32 v[182:183], v[224:225], v[182:183], v[228:229]
	v_cvt_pk_bf16_f32 v184, v180, v181
	v_cvt_pk_bf16_f32 v185, v182, v183
	ds_write_b64 v116, v[184:185] offset:1024
	s_waitcnt lgkmcnt(7)
	v_sub_f32_e32 v186, v4, v164
	v_sub_f32_e32 v187, v9, v164
	v_sub_f32_e32 v188, v6, v164
	v_sub_f32_e32 v189, v7, v164
	v_pk_mul_f32 v[186:187], v[186:187], v[164:165] op_sel:[0,1]
	v_pk_mul_f32 v[188:189], v[188:189], v[164:165] op_sel:[0,1]
	v_pk_fma_f32 v[186:187], v[222:223], v[186:187], v[226:227]
	v_pk_fma_f32 v[188:189], v[224:225], v[188:189], v[228:229]
	v_cvt_pk_bf16_f32 v190, v186, v187
	v_cvt_pk_bf16_f32 v191, v188, v189
	ds_write_b64 v116, v[190:191] offset:5632
	s_waitcnt lgkmcnt(7)
	v_sub_f32_e32 v180, v8, v166
	v_sub_f32_e32 v181, v13, v166
	v_sub_f32_e32 v182, v10, v166
	v_sub_f32_e32 v183, v11, v166
	v_pk_mul_f32 v[180:181], v[180:181], v[166:167] op_sel:[0,1]
	v_pk_mul_f32 v[182:183], v[182:183], v[166:167] op_sel:[0,1]
	v_pk_fma_f32 v[180:181], v[222:223], v[180:181], v[226:227]
	v_pk_fma_f32 v[182:183], v[224:225], v[182:183], v[228:229]
	v_cvt_pk_bf16_f32 v184, v180, v181
	v_cvt_pk_bf16_f32 v185, v182, v183
	ds_write_b64 v116, v[184:185] offset:10240
	s_waitcnt lgkmcnt(7)
	v_sub_f32_e32 v186, v12, v168
	v_sub_f32_e32 v187, v17, v168
	v_sub_f32_e32 v188, v14, v168
	v_sub_f32_e32 v189, v15, v168
	v_pk_mul_f32 v[186:187], v[186:187], v[168:169] op_sel:[0,1]
	v_pk_mul_f32 v[188:189], v[188:189], v[168:169] op_sel:[0,1]
	v_pk_fma_f32 v[186:187], v[222:223], v[186:187], v[226:227]
	v_pk_fma_f32 v[188:189], v[224:225], v[188:189], v[228:229]
	v_cvt_pk_bf16_f32 v190, v186, v187
	v_cvt_pk_bf16_f32 v191, v188, v189
	ds_write_b64 v116, v[190:191] offset:14848
	s_waitcnt lgkmcnt(7)
	v_sub_f32_e32 v180, v16, v170
	v_sub_f32_e32 v181, v21, v170
	v_sub_f32_e32 v182, v18, v170
	v_sub_f32_e32 v183, v19, v170
	v_pk_mul_f32 v[180:181], v[180:181], v[170:171] op_sel:[0,1]
	v_pk_mul_f32 v[182:183], v[182:183], v[170:171] op_sel:[0,1]
	v_pk_fma_f32 v[180:181], v[222:223], v[180:181], v[226:227]
	v_pk_fma_f32 v[182:183], v[224:225], v[182:183], v[228:229]
	v_cvt_pk_bf16_f32 v184, v180, v181
	v_cvt_pk_bf16_f32 v185, v182, v183
	ds_write_b64 v116, v[184:185] offset:19456
	s_waitcnt lgkmcnt(7)
	v_sub_f32_e32 v186, v20, v172
	v_sub_f32_e32 v187, v25, v172
	v_sub_f32_e32 v188, v22, v172
	v_sub_f32_e32 v189, v23, v172
	v_pk_mul_f32 v[186:187], v[186:187], v[172:173] op_sel:[0,1]
	v_pk_mul_f32 v[188:189], v[188:189], v[172:173] op_sel:[0,1]
	v_pk_fma_f32 v[186:187], v[222:223], v[186:187], v[226:227]
	v_pk_fma_f32 v[188:189], v[224:225], v[188:189], v[228:229]
	v_cvt_pk_bf16_f32 v190, v186, v187
	v_cvt_pk_bf16_f32 v191, v188, v189
	ds_write_b64 v116, v[190:191] offset:24064
	s_waitcnt lgkmcnt(7)
	v_sub_f32_e32 v180, v24, v174
	v_sub_f32_e32 v181, v29, v174
	v_sub_f32_e32 v182, v26, v174
	v_sub_f32_e32 v183, v27, v174
	v_pk_mul_f32 v[180:181], v[180:181], v[174:175] op_sel:[0,1]
	v_pk_mul_f32 v[182:183], v[182:183], v[174:175] op_sel:[0,1]
	v_pk_fma_f32 v[180:181], v[222:223], v[180:181], v[226:227]
	v_pk_fma_f32 v[182:183], v[224:225], v[182:183], v[228:229]
	v_cvt_pk_bf16_f32 v184, v180, v181
	v_cvt_pk_bf16_f32 v185, v182, v183
	ds_write_b64 v116, v[184:185] offset:28672
	s_waitcnt lgkmcnt(7)
	v_sub_f32_e32 v186, v28, v176
	v_sub_f32_e32 v187, v33, v176
	v_sub_f32_e32 v188, v30, v176
	v_sub_f32_e32 v189, v31, v176
	v_pk_mul_f32 v[186:187], v[186:187], v[176:177] op_sel:[0,1]
	v_pk_mul_f32 v[188:189], v[188:189], v[176:177] op_sel:[0,1]
	v_pk_fma_f32 v[186:187], v[222:223], v[186:187], v[226:227]
	v_pk_fma_f32 v[188:189], v[224:225], v[188:189], v[228:229]
	v_cvt_pk_bf16_f32 v190, v186, v187
	v_cvt_pk_bf16_f32 v191, v188, v189
	ds_write_b64 v116, v[190:191] offset:33280
	s_waitcnt lgkmcnt(0)
	s_barrier
; #define LAS __attribute__((address_space(3)))
; __device__ __forceinline__ float bf2f(unsigned short b) { return __uint_as_float(((unsigned)b) << 16); }
; #define MFMA16(a_, b_, c_) __builtin_amdgcn_mfma_f32_16x16x32_bf16((a_), (b_), (c_), 0, 0, 0)
; __device__ __forceinline__ s16x4 tr_read(LAS unsigned char* p) { return __builtin_bit_cast(s16x4, __builtin_amdgcn_ds_read_tr16_b64_v4i16((LAS v4i16_t*)p)); }
; __device__ __forceinline__ void gate_prompt_unit(ArgsK& a, LAS unsigned char* lds, int n, int tid, int wave, int lane) {
;     ...
;         __syncthreads();
;         if (g + 1 < 8) {
; #pragma unroll
;             for (int i = 0; i < 8; ++i) xr[i] = ({ const u32x2 w_ = __builtin_nontemporal_load((const u32x2*)(VR + (r0 + srb + 16 * i) * DM + (g + 1) * 128 + sch * 4)); (f32x4){bf2f(w_.x & 0xffff), bf2f(w_.x >> 16), bf2f(w_.y & 0xffff), bf2f(w_.y >> 16)}; }); }
;         u32x2 uw[8];
; #pragma unroll
;         for (int cb = 0; cb < 8; ++cb) uw[cb] = __builtin_nontemporal_load((const u32x2*)(U + (r0 + t) * DM + g * 128 + cb * 16 + quad * 4));
;         f32x4 acc[8];
; #pragma unroll
;         for (int cb = 0; cb < 8; ++cb) acc[cb] = (f32x4){0.f, 0.f, 0.f, 0.f};
;         for (int c = 0; c < nch; ++c) { const bf16_t* wp = WSM + ((size_t)(g * 128 + t)) * 128 + 32 * c + quad * 4;
;             const u32x2 w1 = *(const u32x2*)wp, w2 = *(const u32x2*)(wp + 16); const bf16x8 wf = __builtin_bit_cast(bf16x8, ((u32x4){w1.x, w1.y, w2.x, w2.y}));
; #pragma unroll
;             for (int cb = 0; cb < 8; ++cb) { LAS unsigned char* vp = lds + GT_V + (32 * c + quad * 4 + (l15 >> 2)) * GT_VSTR + cb * 32 + (lane & 3) * 8;
;                 const s16x4 r1 = tr_read(vp), r2 = tr_read(vp + 16 * GT_VSTR);
;                 acc[cb] = MFMA16(((bf16x8){r1[0], r1[1], r1[2], r1[3], r2[0], r2[1], r2[2], r2[3]}), wf, acc[cb]); } }
	s_min_u32 s4, s3, 7
	s_mov_b32 s5, 0
	s_lshl_b32 s4, s4, 8
	v_lshl_add_u64 v[138:139], v[86:87], 0, s[4:5]
	global_load_dwordx2 v[206:207], v[138:139], off nt
	s_add_u32 s4, s4, 0x8000
	v_lshl_add_u64 v[138:139], v[86:87], 0, s[4:5]
	global_load_dwordx2 v[208:209], v[138:139], off nt
	s_add_u32 s4, s4, 0x8000
	v_lshl_add_u64 v[138:139], v[86:87], 0, s[4:5]
	global_load_dwordx2 v[210:211], v[138:139], off nt
	s_add_u32 s4, s4, 0x8000
	v_lshl_add_u64 v[138:139], v[86:87], 0, s[4:5]
	global_load_dwordx2 v[212:213], v[138:139], off nt
	s_add_u32 s4, s4, 0x8000
	v_lshl_add_u64 v[138:139], v[86:87], 0, s[4:5]
	global_load_dwordx2 v[214:215], v[138:139], off nt
	s_add_u32 s4, s4, 0x8000
	v_lshl_add_u64 v[138:139], v[86:87], 0, s[4:5]
	global_load_dwordx2 v[216:217], v[138:139], off nt
	s_add_u32 s4, s4, 0x8000
	v_lshl_add_u64 v[138:139], v[86:87], 0, s[4:5]
	global_load_dwordx2 v[218:219], v[138:139], off nt
	s_add_u32 s4, s4, 0x8000
	v_lshl_add_u64 v[138:139], v[86:87], 0, s[4:5]
	global_load_dwordx2 v[220:221], v[138:139], off nt
	s_lshl_b32 s4, s12, 1
	v_lshl_add_u64 v[140:141], v[90:91], 0, s[4:5]
	v_mov_b32_e32 v34, 0
	v_mov_b32_e32 v35, 0
	v_mov_b32_e32 v36, 0
	v_mov_b32_e32 v37, 0
	v_mov_b32_e32 v38, 0
	v_mov_b32_e32 v39, 0
	v_mov_b32_e32 v40, 0
	v_mov_b32_e32 v41, 0
	v_mov_b32_e32 v42, 0
	v_mov_b32_e32 v43, 0
	v_mov_b32_e32 v44, 0
	v_mov_b32_e32 v45, 0
	v_mov_b32_e32 v46, 0
	v_mov_b32_e32 v47, 0
	v_mov_b32_e32 v48, 0
	v_mov_b32_e32 v49, 0
	v_mov_b32_e32 v50, 0
	v_mov_b32_e32 v51, 0
	v_mov_b32_e32 v52, 0
	v_mov_b32_e32 v53, 0
	v_mov_b32_e32 v54, 0
	v_mov_b32_e32 v55, 0
	v_mov_b32_e32 v56, 0
	v_mov_b32_e32 v57, 0
	v_mov_b32_e32 v58, 0
	v_mov_b32_e32 v59, 0
	v_mov_b32_e32 v60, 0
	v_mov_b32_e32 v61, 0
	v_mov_b32_e32 v62, 0
	v_mov_b32_e32 v63, 0
	v_mov_b32_e32 v64, 0
	v_mov_b32_e32 v65, 0
	ds_read_b64_tr_b16 v[130:131], v137 offset:0
	ds_read_b64_tr_b16 v[132:133], v137 offset:4608
	s_waitcnt vmcnt(25)
	ds_read_b64_tr_b16 v[142:143], v137 offset:32
	ds_read_b64_tr_b16 v[144:145], v137 offset:4640
	s_waitcnt lgkmcnt(2)
	v_mfma_f32_16x16x32_bf16 v[38:41], v[130:133], v[230:233], v[38:41]
	ds_read_b64_tr_b16 v[130:131], v137 offset:64
	ds_read_b64_tr_b16 v[132:133], v137 offset:4672
	s_waitcnt lgkmcnt(2)
	v_mfma_f32_16x16x32_bf16 v[42:45], v[142:145], v[230:233], v[42:45]
	ds_read_b64_tr_b16 v[142:143], v137 offset:96
	ds_read_b64_tr_b16 v[144:145], v137 offset:4704
	s_waitcnt lgkmcnt(2)
	v_mfma_f32_16x16x32_bf16 v[46:49], v[130:133], v[230:233], v[46:49]
	ds_read_b64_tr_b16 v[130:131], v137 offset:128
	ds_read_b64_tr_b16 v[132:133], v137 offset:4736
	s_waitcnt lgkmcnt(2)
	v_mfma_f32_16x16x32_bf16 v[50:53], v[142:145], v[230:233], v[50:53]
	ds_read_b64_tr_b16 v[142:143], v137 offset:160
	ds_read_b64_tr_b16 v[144:145], v137 offset:4768
	s_waitcnt lgkmcnt(2)
	v_mfma_f32_16x16x32_bf16 v[54:57], v[130:133], v[230:233], v[54:57]
	ds_read_b64_tr_b16 v[130:131], v137 offset:192
	ds_read_b64_tr_b16 v[132:133], v137 offset:4800
	s_waitcnt lgkmcnt(2)
	v_mfma_f32_16x16x32_bf16 v[58:61], v[142:145], v[230:233], v[58:61]
	ds_read_b64_tr_b16 v[142:143], v137 offset:224
	ds_read_b64_tr_b16 v[144:145], v137 offset:4832
	s_waitcnt lgkmcnt(2)
	v_mfma_f32_16x16x32_bf16 v[62:65], v[130:133], v[230:233], v[62:65]
	s_waitcnt lgkmcnt(0)
	v_mfma_f32_16x16x32_bf16 v[34:37], v[142:145], v[230:233], v[34:37]
	ds_read_b64_tr_b16 v[130:131], v137 offset:9216
	ds_read_b64_tr_b16 v[132:133], v137 offset:13824
	s_waitcnt vmcnt(23)
	ds_read_b64_tr_b16 v[142:143], v137 offset:9248
	ds_read_b64_tr_b16 v[144:145], v137 offset:13856
	s_waitcnt lgkmcnt(2)
	v_mfma_f32_16x16x32_bf16 v[38:41], v[130:133], v[234:237], v[38:41]
	ds_read_b64_tr_b16 v[130:131], v137 offset:9280
	ds_read_b64_tr_b16 v[132:133], v137 offset:13888
	s_waitcnt lgkmcnt(2)
	v_mfma_f32_16x16x32_bf16 v[42:45], v[142:145], v[234:237], v[42:45]
	ds_read_b64_tr_b16 v[142:143], v137 offset:9312
	ds_read_b64_tr_b16 v[144:145], v137 offset:13920
	s_waitcnt lgkmcnt(2)
	v_mfma_f32_16x16x32_bf16 v[46:49], v[130:133], v[234:237], v[46:49]
	ds_read_b64_tr_b16 v[130:131], v137 offset:9344
	ds_read_b64_tr_b16 v[132:133], v137 offset:13952
	s_waitcnt lgkmcnt(2)
	v_mfma_f32_16x16x32_bf16 v[50:53], v[142:145], v[234:237], v[50:53]
	ds_read_b64_tr_b16 v[142:143], v137 offset:9376
	ds_read_b64_tr_b16 v[144:145], v137 offset:13984
	s_waitcnt lgkmcnt(2)
	v_mfma_f32_16x16x32_bf16 v[54:57], v[130:133], v[234:237], v[54:57]
	ds_read_b64_tr_b16 v[130:131], v137 offset:9408
	ds_read_b64_tr_b16 v[132:133], v137 offset:14016
	s_waitcnt lgkmcnt(2)
	v_mfma_f32_16x16x32_bf16 v[58:61], v[142:145], v[234:237], v[58:61]
	ds_read_b64_tr_b16 v[142:143], v137 offset:9440
	ds_read_b64_tr_b16 v[144:145], v137 offset:14048
	s_waitcnt lgkmcnt(2)
	v_mfma_f32_16x16x32_bf16 v[62:65], v[130:133], v[234:237], v[62:65]
	s_waitcnt lgkmcnt(0)
	v_mfma_f32_16x16x32_bf16 v[34:37], v[142:145], v[234:237], v[34:37]
	s_cmp_eq_u32 s15, 2
	s_cbranch_scc1 .Lgate_cdone
; #define LAS __attribute__((address_space(3)))
; #define MFMA16(a_, b_, c_) __builtin_amdgcn_mfma_f32_16x16x32_bf16((a_), (b_), (c_), 0, 0, 0)
; __device__ __forceinline__ s16x4 tr_read(LAS unsigned char* p) { return __builtin_bit_cast(s16x4, __builtin_amdgcn_ds_read_tr16_b64_v4i16((LAS v4i16_t*)p)); }
; __device__ __forceinline__ void gate_prompt_unit(ArgsK& a, LAS unsigned char* lds, int n, int tid, int wave, int lane) {
;     ...
;         for (int c = 0; c < nch; ++c) { const bf16_t* wp = WSM + ((size_t)(g * 128 + t)) * 128 + 32 * c + quad * 4;
;             const u32x2 w1 = *(const u32x2*)wp, w2 = *(const u32x2*)(wp + 16); const bf16x8 wf = __builtin_bit_cast(bf16x8, ((u32x4){w1.x, w1.y, w2.x, w2.y}));
; #pragma unroll
;             for (int cb = 0; cb < 8; ++cb) { LAS unsigned char* vp = lds + GT_V + (32 * c + quad * 4 + (l15 >> 2)) * GT_VSTR + cb * 32 + (lane & 3) * 8;
;                 const s16x4 r1 = tr_read(vp), r2 = tr_read(vp + 16 * GT_VSTR);
;                 acc[cb] = MFMA16(((bf16x8){r1[0], r1[1], r1[2], r1[3], r2[0], r2[1], r2[2], r2[3]}), wf, acc[cb]); } }
	ds_read_b64_tr_b16 v[130:131], v137 offset:18432
	ds_read_b64_tr_b16 v[132:133], v137 offset:23040
	s_waitcnt vmcnt(21)
	ds_read_b64_tr_b16 v[142:143], v137 offset:18464
	ds_read_b64_tr_b16 v[144:145], v137 offset:23072
	s_waitcnt lgkmcnt(2)
	v_mfma_f32_16x16x32_bf16 v[38:41], v[130:133], v[238:241], v[38:41]
	ds_read_b64_tr_b16 v[130:131], v137 offset:18496
	ds_read_b64_tr_b16 v[132:133], v137 offset:23104
	s_waitcnt lgkmcnt(2)
	v_mfma_f32_16x16x32_bf16 v[42:45], v[142:145], v[238:241], v[42:45]
	ds_read_b64_tr_b16 v[142:143], v137 offset:18528
	ds_read_b64_tr_b16 v[144:145], v137 offset:23136
	s_waitcnt lgkmcnt(2)
	v_mfma_f32_16x16x32_bf16 v[46:49], v[130:133], v[238:241], v[46:49]
	ds_read_b64_tr_b16 v[130:131], v137 offset:18560
	ds_read_b64_tr_b16 v[132:133], v137 offset:23168
	s_waitcnt lgkmcnt(2)
	v_mfma_f32_16x16x32_bf16 v[50:53], v[142:145], v[238:241], v[50:53]
	ds_read_b64_tr_b16 v[142:143], v137 offset:18592
	ds_read_b64_tr_b16 v[144:145], v137 offset:23200
	s_waitcnt lgkmcnt(2)
	v_mfma_f32_16x16x32_bf16 v[54:57], v[130:133], v[238:241], v[54:57]
	ds_read_b64_tr_b16 v[130:131], v137 offset:18624
	ds_read_b64_tr_b16 v[132:133], v137 offset:23232
	s_waitcnt lgkmcnt(2)
	v_mfma_f32_16x16x32_bf16 v[58:61], v[142:145], v[238:241], v[58:61]
	ds_read_b64_tr_b16 v[142:143], v137 offset:18656
	ds_read_b64_tr_b16 v[144:145], v137 offset:23264
	s_waitcnt lgkmcnt(2)
	v_mfma_f32_16x16x32_bf16 v[62:65], v[130:133], v[238:241], v[62:65]
	s_waitcnt lgkmcnt(0)
	v_mfma_f32_16x16x32_bf16 v[34:37], v[142:145], v[238:241], v[34:37]
	ds_read_b64_tr_b16 v[130:131], v137 offset:27648
	ds_read_b64_tr_b16 v[132:133], v137 offset:32256
	s_waitcnt vmcnt(19)
	ds_read_b64_tr_b16 v[142:143], v137 offset:27680
	ds_read_b64_tr_b16 v[144:145], v137 offset:32288
	s_waitcnt lgkmcnt(2)
	v_mfma_f32_16x16x32_bf16 v[38:41], v[130:133], v[242:245], v[38:41]
	ds_read_b64_tr_b16 v[130:131], v137 offset:27712
	ds_read_b64_tr_b16 v[132:133], v137 offset:32320
	s_waitcnt lgkmcnt(2)
	v_mfma_f32_16x16x32_bf16 v[42:45], v[142:145], v[242:245], v[42:45]
	ds_read_b64_tr_b16 v[142:143], v137 offset:27744
	ds_read_b64_tr_b16 v[144:145], v137 offset:32352
	s_waitcnt lgkmcnt(2)
	v_mfma_f32_16x16x32_bf16 v[46:49], v[130:133], v[242:245], v[46:49]
	ds_read_b64_tr_b16 v[130:131], v137 offset:27776
	ds_read_b64_tr_b16 v[132:133], v137 offset:32384
	s_waitcnt lgkmcnt(2)
	v_mfma_f32_16x16x32_bf16 v[50:53], v[142:145], v[242:245], v[50:53]
	ds_read_b64_tr_b16 v[142:143], v137 offset:27808
	ds_read_b64_tr_b16 v[144:145], v137 offset:32416
	s_waitcnt lgkmcnt(2)
	v_mfma_f32_16x16x32_bf16 v[54:57], v[130:133], v[242:245], v[54:57]
	ds_read_b64_tr_b16 v[130:131], v137 offset:27840
	ds_read_b64_tr_b16 v[132:133], v137 offset:32448
	s_waitcnt lgkmcnt(2)
	v_mfma_f32_16x16x32_bf16 v[58:61], v[142:145], v[242:245], v[58:61]
	ds_read_b64_tr_b16 v[142:143], v137 offset:27872
	ds_read_b64_tr_b16 v[144:145], v137 offset:32480
	s_waitcnt lgkmcnt(2)
	v_mfma_f32_16x16x32_bf16 v[62:65], v[130:133], v[242:245], v[62:65]
	s_waitcnt lgkmcnt(0)
	v_mfma_f32_16x16x32_bf16 v[34:37], v[142:145], v[242:245], v[34:37]
; __device__ __forceinline__ unsigned cvt_pk_bf16(float lo, float hi) { unsigned r; asm volatile("v_cvt_pk_bf16_f32 %0, %1, %2" : "=v"(r) : "v"(lo), "v"(hi)); return r; }
; #define LAS __attribute__((address_space(3)))
; __device__ __forceinline__ float bf2f(unsigned short b) { return __uint_as_float(((unsigned)b) << 16); }
; #define MFMA16(a_, b_, c_) __builtin_amdgcn_mfma_f32_16x16x32_bf16((a_), (b_), (c_), 0, 0, 0)
; __device__ __forceinline__ s16x4 tr_read(LAS unsigned char* p) { return __builtin_bit_cast(s16x4, __builtin_amdgcn_ds_read_tr16_b64_v4i16((LAS v4i16_t*)p)); }
; __device__ __forceinline__ void gate_prompt_unit(ArgsK& a, LAS unsigned char* lds, int n, int tid, int wave, int lane) {
;     ...
;             for (int i = 0; i < 8; ++i) xr[i] = ({ const u32x2 w_ = __builtin_nontemporal_load((const u32x2*)(VR + (r0 + srb + 16 * i) * DM + (g + 1) * 128 + sch * 4)); (f32x4){bf2f(w_.x & 0xffff), bf2f(w_.x >> 16), bf2f(w_.y & 0xffff), bf2f(w_.y >> 16)}; }); }
;         u32x2 uw[8];
; #pragma unroll
;         for (int cb = 0; cb < 8; ++cb) uw[cb] = __builtin_nontemporal_load((const u32x2*)(U + (r0 + t) * DM + g * 128 + cb * 16 + quad * 4));
;         f32x4 acc[8];
; #pragma unroll
;         for (int cb = 0; cb < 8; ++cb) acc[cb] = (f32x4){0.f, 0.f, 0.f, 0.f};
;         for (int c = 0; c < nch; ++c) { const bf16_t* wp = WSM + ((size_t)(g * 128 + t)) * 128 + 32 * c + quad * 4;
;             const u32x2 w1 = *(const u32x2*)wp, w2 = *(const u32x2*)(wp + 16); const bf16x8 wf = __builtin_bit_cast(bf16x8, ((u32x4){w1.x, w1.y, w2.x, w2.y}));
; #pragma unroll
;             for (int cb = 0; cb < 8; ++cb) { LAS unsigned char* vp = lds + GT_V + (32 * c + quad * 4 + (l15 >> 2)) * GT_VSTR + cb * 32 + (lane & 3) * 8;
;                 const s16x4 r1 = tr_read(vp), r2 = tr_read(vp + 16 * GT_VSTR);
;                 acc[cb] = MFMA16(((bf16x8){r1[0], r1[1], r1[2], r1[3], r2[0], r2[1], r2[2], r2[3]}), wf, acc[cb]); } }
;         const float bias = a.in[28][g * 128 + t];
; #pragma unroll
;         for (int cb = 0; cb < 8; ++cb) { const size_t off = (r0 + t) * DM + g * 128 + cb * 16 + quad * 4;
;             const f32x4 sp = acc[cb] + bias; u32x2 w; w.x = cvt_pk_bf16(bf2f(uw[cb].x & 0xffff) * sp[0], bf2f(uw[cb].x >> 16) * sp[1]); w.y = cvt_pk_bf16(bf2f(uw[cb].y & 0xffff) * sp[2], bf2f(uw[cb].y >> 16) * sp[3]);
;             *(u32x2*)(UG + off) = w; }
;         __syncthreads();
.Lgate_cdone:
	s_waitcnt vmcnt(8)
	s_nop 4
	v_pk_add_f32 v[38:39], v[38:39], v[246:247] op_sel_hi:[1,0]
	v_pk_add_f32 v[40:41], v[40:41], v[246:247] op_sel_hi:[1,0]
	v_lshlrev_b32_e32 v180, 16, v106
	v_and_b32_e32 v181, 0xffff0000, v106
	v_lshlrev_b32_e32 v182, 16, v107
	v_and_b32_e32 v183, 0xffff0000, v107
	v_mul_f32_e32 v38, v38, v180
	v_mul_f32_e32 v39, v39, v181
	v_mul_f32_e32 v40, v40, v182
	v_mul_f32_e32 v41, v41, v183
	v_cvt_pk_bf16_f32 v184, v38, v39
	v_cvt_pk_bf16_f32 v185, v40, v41
	global_store_dwordx2 v[140:141], v[184:185], off
	v_pk_add_f32 v[42:43], v[42:43], v[246:247] op_sel_hi:[1,0]
	v_pk_add_f32 v[44:45], v[44:45], v[246:247] op_sel_hi:[1,0]
	v_lshlrev_b32_e32 v186, 16, v104
	v_and_b32_e32 v187, 0xffff0000, v104
	v_lshlrev_b32_e32 v188, 16, v105
	v_and_b32_e32 v189, 0xffff0000, v105
	v_mul_f32_e32 v42, v42, v186
	v_mul_f32_e32 v43, v43, v187
	v_mul_f32_e32 v44, v44, v188
	v_mul_f32_e32 v45, v45, v189
	v_cvt_pk_bf16_f32 v190, v42, v43
	v_cvt_pk_bf16_f32 v191, v44, v45
	global_store_dwordx2 v[140:141], v[190:191], off offset:32
	v_pk_add_f32 v[46:47], v[46:47], v[246:247] op_sel_hi:[1,0]
	v_pk_add_f32 v[48:49], v[48:49], v[246:247] op_sel_hi:[1,0]
	v_lshlrev_b32_e32 v180, 16, v102
	v_and_b32_e32 v181, 0xffff0000, v102
	v_lshlrev_b32_e32 v182, 16, v103
	v_and_b32_e32 v183, 0xffff0000, v103
	v_mul_f32_e32 v46, v46, v180
	v_mul_f32_e32 v47, v47, v181
	v_mul_f32_e32 v48, v48, v182
	v_mul_f32_e32 v49, v49, v183
	v_cvt_pk_bf16_f32 v184, v46, v47
	v_cvt_pk_bf16_f32 v185, v48, v49
	global_store_dwordx2 v[140:141], v[184:185], off offset:64
	v_pk_add_f32 v[50:51], v[50:51], v[246:247] op_sel_hi:[1,0]
	v_pk_add_f32 v[52:53], v[52:53], v[246:247] op_sel_hi:[1,0]
	v_lshlrev_b32_e32 v186, 16, v100
	v_and_b32_e32 v187, 0xffff0000, v100
	v_lshlrev_b32_e32 v188, 16, v101
	v_and_b32_e32 v189, 0xffff0000, v101
	v_mul_f32_e32 v50, v50, v186
	v_mul_f32_e32 v51, v51, v187
	v_mul_f32_e32 v52, v52, v188
	v_mul_f32_e32 v53, v53, v189
	v_cvt_pk_bf16_f32 v190, v50, v51
	v_cvt_pk_bf16_f32 v191, v52, v53
	global_store_dwordx2 v[140:141], v[190:191], off offset:96
	v_pk_add_f32 v[54:55], v[54:55], v[246:247] op_sel_hi:[1,0]
	v_pk_add_f32 v[56:57], v[56:57], v[246:247] op_sel_hi:[1,0]
	v_lshlrev_b32_e32 v180, 16, v98
	v_and_b32_e32 v181, 0xffff0000, v98
	v_lshlrev_b32_e32 v182, 16, v99
	v_and_b32_e32 v183, 0xffff0000, v99
	v_mul_f32_e32 v54, v54, v180
	v_mul_f32_e32 v55, v55, v181
	v_mul_f32_e32 v56, v56, v182
	v_mul_f32_e32 v57, v57, v183
	v_cvt_pk_bf16_f32 v184, v54, v55
	v_cvt_pk_bf16_f32 v185, v56, v57
	global_store_dwordx2 v[140:141], v[184:185], off offset:128
	v_pk_add_f32 v[58:59], v[58:59], v[246:247] op_sel_hi:[1,0]
	v_pk_add_f32 v[60:61], v[60:61], v[246:247] op_sel_hi:[1,0]
	v_lshlrev_b32_e32 v186, 16, v96
	v_and_b32_e32 v187, 0xffff0000, v96
	v_lshlrev_b32_e32 v188, 16, v97
	v_and_b32_e32 v189, 0xffff0000, v97
	v_mul_f32_e32 v58, v58, v186
	v_mul_f32_e32 v59, v59, v187
	v_mul_f32_e32 v60, v60, v188
	v_mul_f32_e32 v61, v61, v189
	v_cvt_pk_bf16_f32 v190, v58, v59
	v_cvt_pk_bf16_f32 v191, v60, v61
	global_store_dwordx2 v[140:141], v[190:191], off offset:160
	v_pk_add_f32 v[62:63], v[62:63], v[246:247] op_sel_hi:[1,0]
	v_pk_add_f32 v[64:65], v[64:65], v[246:247] op_sel_hi:[1,0]
	v_lshlrev_b32_e32 v180, 16, v94
	v_and_b32_e32 v181, 0xffff0000, v94
	v_lshlrev_b32_e32 v182, 16, v95
	v_and_b32_e32 v183, 0xffff0000, v95
	v_mul_f32_e32 v62, v62, v180
	v_mul_f32_e32 v63, v63, v181
	v_mul_f32_e32 v64, v64, v182
	v_mul_f32_e32 v65, v65, v183
	v_cvt_pk_bf16_f32 v184, v62, v63
	v_cvt_pk_bf16_f32 v185, v64, v65
	global_store_dwordx2 v[140:141], v[184:185], off offset:192
	v_pk_add_f32 v[34:35], v[34:35], v[246:247] op_sel_hi:[1,0]
	v_pk_add_f32 v[36:37], v[36:37], v[246:247] op_sel_hi:[1,0]
	v_lshlrev_b32_e32 v186, 16, v92
	v_and_b32_e32 v187, 0xffff0000, v92
	v_lshlrev_b32_e32 v188, 16, v93
	v_and_b32_e32 v189, 0xffff0000, v93
	v_mul_f32_e32 v34, v34, v186
	v_mul_f32_e32 v35, v35, v187
	v_mul_f32_e32 v36, v36, v188
	v_mul_f32_e32 v37, v37, v189
	v_cvt_pk_bf16_f32 v190, v34, v35
	v_cvt_pk_bf16_f32 v191, v36, v37
	global_store_dwordx2 v[140:141], v[190:191], off offset:224
	s_min_u32 s12, s3, 7
	s_lshl_b32 s4, s12, 7
	v_add_u32_e32 v108, s4, v74
	v_ashrrev_i32_e32 v109, 31, v108
	v_lshlrev_b64 v[138:139], 8, v[108:109]
	v_lshl_add_u64 v[110:111], v[82:83], 0, v[138:139]
	global_load_dwordx2 v[230:231], v[110:111], off
	global_load_dwordx2 v[232:233], v[110:111], off offset:32
	global_load_dwordx2 v[234:235], v[110:111], off offset:64
	global_load_dwordx2 v[236:237], v[110:111], off offset:96
	global_load_dwordx2 v[238:239], v[110:111], off offset:128
	global_load_dwordx2 v[240:241], v[110:111], off offset:160
	global_load_dwordx2 v[242:243], v[110:111], off offset:192
	global_load_dwordx2 v[244:245], v[110:111], off offset:224
	v_lshl_add_u64 v[108:109], v[108:109], 2, s[6:7]
	global_load_dword v246, v[108:109], off
	s_mov_b32 s5, 0
	s_lshl_b32 s4, s12, 9
	v_lshl_add_u64 v[138:139], v[76:77], 0, s[4:5]
	global_load_dwordx4 v[222:225], v[138:139], off
	v_lshl_add_u64 v[138:139], v[78:79], 0, s[4:5]
	global_load_dwordx4 v[226:229], v[138:139], off
	s_lshl_b32 s4, s12, 8
	v_lshl_add_u64 v[138:139], v[88:89], 0, s[4:5]
	global_load_dwordx2 v[106:107], v[138:139], off nt
	global_load_dwordx2 v[104:105], v[138:139], off offset:32 nt
	global_load_dwordx2 v[102:103], v[138:139], off offset:64 nt
	global_load_dwordx2 v[100:101], v[138:139], off offset:96 nt
	global_load_dwordx2 v[98:99], v[138:139], off offset:128 nt
	global_load_dwordx2 v[96:97], v[138:139], off offset:160 nt
	global_load_dwordx2 v[94:95], v[138:139], off offset:192 nt
	global_load_dwordx2 v[92:93], v[138:139], off offset:224 nt
	s_waitcnt vmcnt(27)
	v_lshlrev_b32_e32 v0, 16, v206
	v_and_b32_e32 v5, 0xffff0000, v206
	v_lshlrev_b32_e32 v2, 16, v207
	v_and_b32_e32 v3, 0xffff0000, v207
	v_lshlrev_b32_e32 v4, 16, v208
	v_and_b32_e32 v9, 0xffff0000, v208
	v_lshlrev_b32_e32 v6, 16, v209
	v_and_b32_e32 v7, 0xffff0000, v209
	v_lshlrev_b32_e32 v8, 16, v210
	v_and_b32_e32 v13, 0xffff0000, v210
	v_lshlrev_b32_e32 v10, 16, v211
	v_and_b32_e32 v11, 0xffff0000, v211
	v_lshlrev_b32_e32 v12, 16, v212
	v_and_b32_e32 v17, 0xffff0000, v212
	v_lshlrev_b32_e32 v14, 16, v213
	v_and_b32_e32 v15, 0xffff0000, v213
	v_lshlrev_b32_e32 v16, 16, v214
	v_and_b32_e32 v21, 0xffff0000, v214
	v_lshlrev_b32_e32 v18, 16, v215
	v_and_b32_e32 v19, 0xffff0000, v215
	v_lshlrev_b32_e32 v20, 16, v216
	v_and_b32_e32 v25, 0xffff0000, v216
	v_lshlrev_b32_e32 v22, 16, v217
	v_and_b32_e32 v23, 0xffff0000, v217
	v_lshlrev_b32_e32 v24, 16, v218
	v_and_b32_e32 v29, 0xffff0000, v218
	v_lshlrev_b32_e32 v26, 16, v219
	v_and_b32_e32 v27, 0xffff0000, v219
	v_lshlrev_b32_e32 v28, 16, v220
	v_and_b32_e32 v33, 0xffff0000, v220
	v_lshlrev_b32_e32 v30, 16, v221
	v_and_b32_e32 v31, 0xffff0000, v221
	s_cmp_eq_u32 s3, 8
	s_barrier
	s_cbranch_scc0 .LBB0_142
	s_add_i32 s2, s2, s23
	s_cmpk_gt_i32 s2, 0x1ff
	s_cbranch_scc0 .LBB0_109

; __device__ __forceinline__ void attn_prompt_unit(ArgsK& a, LAS unsigned char* lds, int b, int h, int qb, int tid, int wave, int lane) {
;     ...
;         const bool more = kt + 1 < NT;
;         if (kt + 2 < NT) { const size_t r = rowb + (kt + 2) * 64 + skey; kreg2 = *(const u32x4*)(KB + r * 512 + h * 64 + sch * 8); vreg2 = *(const u32x4*)(VB + r * 512 + h * 64 + sch * 8);
;             if (tid < 64) ckreg2 = CUM[(rowb + (kt + 2) * 64 + tid) * 8 + h] * LOG2E; }
;     ...
;         kreg = kreg2; vreg = vreg2; ckreg = ckreg2;
.LBB0_244:
	s_waitcnt vmcnt(1)
	v_mov_b64_e32 v[26:27], v[34:35]
	s_waitcnt vmcnt(0)
	v_mov_b64_e32 v[30:31], v[38:39]
	v_mov_b64_e32 v[28:29], v[36:37]
	v_mov_b64_e32 v[32:33], v[40:41]
	v_mul_f32_e32 v223, 0x3fb8aa3b, v224
	s_cmp_ge_u32 s35, s58
	s_cbranch_scc1 .LBB0_249
.LBB0_245:
	v_add_co_u32_e32 v38, vcc, 0x4080000, v128
	s_nop 1
	v_addc_co_u32_e32 v39, vcc, 0, v129, vcc
	global_load_dwordx4 v[34:37], v[128:129], off
	s_nop 0
	global_load_dwordx4 v[38:41], v[38:39], off
	s_and_saveexec_b64 s[14:15], s[40:41]
	s_cbranch_execz .LBB0_247
	global_load_dword v224, v[170:171], off

; #define LAS __attribute__((address_space(3)))
; __device__ __forceinline__ void attn_prompt_unit(ArgsK& a, LAS unsigned char* lds, int b, int h, int qb, int tid, int wave, int lane) {
;     ...
;         if (more) { *(LAS u32x4*)(bufn + AT_K + skey * 144 + sch * 16) = kreg; *(LAS u32x4*)(bufn + AT_V + skey * 160 + sch * 16) = vreg; if (tid < 64) ((LAS float*)(bufn + AT_CK))[tid] = ckreg; }
.LBB0_253:
	s_bitcmp1_b32 s14, 0
	s_cselect_b32 s14, 0x4d00, 0
	s_add_i32 s65, s14, 0
	v_add3_u32 v0, s65, v117, v207
	s_waitcnt vmcnt(2)
	ds_write_b128 v0, v[26:29]
	v_add3_u32 v0, s65, v208, v207
	s_waitcnt vmcnt(2)
	ds_write_b128 v0, v[30:33] offset:9216
	s_and_saveexec_b64 s[14:15], s[40:41]
	v_lshl_add_u32 v0, v160, 2, s65
	ds_write_b32 v0, v223 offset:19456
	s_or_b64 exec, exec, s[14:15]

; __device__ __forceinline__ void attn_prompt_unit(ArgsK& a, LAS unsigned char* lds, int b, int h, int qb, int tid, int wave, int lane) {
;     ...
;         const bool more = kt + 1 < NT;
;         if (kt + 2 < NT) { const size_t r = rowb + (kt + 2) * 64 + skey; kreg2 = *(const u32x4*)(KB + r * 512 + h * 64 + sch * 8); vreg2 = *(const u32x4*)(VB + r * 512 + h * 64 + sch * 8);
;             if (tid < 64) ckreg2 = CUM[(rowb + (kt + 2) * 64 + tid) * 8 + h] * LOG2E; }
.LBB0_264:
	v_add_co_u32_e32 v38, vcc, 0x4080000, v138
	s_nop 1
	v_addc_co_u32_e32 v39, vcc, 0, v139, vcc
	global_load_dwordx4 v[34:37], v[138:139], off
	s_nop 0
	global_load_dwordx4 v[38:41], v[38:39], off
	s_and_saveexec_b64 s[14:15], s[40:41]
	s_cbranch_execz .LBB0_266
	global_load_dword v180, v[136:137], off

; #define LAS __attribute__((address_space(3)))
; __device__ __forceinline__ void attn_prompt_unit(ArgsK& a, LAS unsigned char* lds, int b, int h, int qb, int tid, int wave, int lane) {
;     ...
;         if (more) { *(LAS u32x4*)(bufn + AT_K + skey * 144 + sch * 16) = kreg; *(LAS u32x4*)(bufn + AT_V + skey * 160 + sch * 16) = vreg; if (tid < 64) ((LAS float*)(bufn + AT_CK))[tid] = ckreg; }
;         kreg = kreg2; vreg = vreg2; ckreg = ckreg2;
.LBB0_270:
	s_add_i32 s18, s18, 1
	s_bitcmp1_b32 s18, 0
	s_cselect_b32 s14, 0x4d00, 0
	s_add_i32 s19, s14, 0
	v_add3_u32 v74, s19, v117, v207
	s_waitcnt vmcnt(3)
	ds_write_b128 v74, v[66:69]
	v_add3_u32 v66, s19, v208, v207
	s_waitcnt vmcnt(2)
	ds_write_b128 v66, v[70:73] offset:9216
	s_and_saveexec_b64 s[14:15], s[40:41]
	v_lshl_add_u32 v66, v160, 2, s19
	ds_write_b32 v66, v181 offset:19456
	s_or_b64 exec, exec, s[14:15]
	s_add_i32 s12, s12, 64
	v_lshl_add_u64 v[136:137], v[136:137], 0, s[26:27]
	s_cmp_lg_u32 s56, s18
	v_lshl_add_u64 v[138:139], v[138:139], 0, s[36:37]
	s_waitcnt lgkmcnt(0)
	s_barrier
	s_cbranch_scc0 .LBB0_274
	s_waitcnt vmcnt(1)
	v_mov_b64_e32 v[68:69], v[36:37]
	s_waitcnt vmcnt(0)
	v_mov_b64_e32 v[72:73], v[40:41]
	v_mov_b64_e32 v[66:67], v[34:35]
	v_mov_b64_e32 v[70:71], v[38:39]
	v_mul_f32_e32 v181, 0x3fb8aa3b, v180
	s_branch .LBB0_264

; #define LAS __attribute__((address_space(3)))
; #define MFMA16(a_, b_, c_) __builtin_amdgcn_mfma_f32_16x16x32_bf16((a_), (b_), (c_), 0, 0, 0)
; __device__ __forceinline__ void attn_prompt_unit(ArgsK& a, LAS unsigned char* lds, int b, int h, int qb, int tid, int wave, int lane) {
;     ...
;         if (kt * 64 <= qw + 31) {
;             const LAS float* CK = (const LAS float*)(bufc + AT_CK);
;             f32x4 st[4][2];
; #pragma unroll
;             for (int kb = 0; kb < 4; ++kb) { const bf16x8 k0 = *(const LAS bf16x8*)(bufc + AT_K + (kb * 16 + l15) * 144 + quad * 16), k1 = *(const LAS bf16x8*)(bufc + AT_K + (kb * 16 + l15) * 144 + 64 + quad * 16);
;                 const f32x4 ckv = *(const LAS f32x4*)(CK + kb * 16 + quad * 4);
; #pragma unroll
;                 for (int qq = 0; qq < 2; ++qq) { const f32x4 ci = (f32x4){cq[qq] - ckv[0], cq[qq] - ckv[1], cq[qq] - ckv[2], cq[qq] - ckv[3]};
;                     st[kb][qq] = MFMA16(k0, qf[qq][0], ci); st[kb][qq] = MFMA16(k1, qf[qq][1], st[kb][qq]); } }
;             if (kt * 64 + 63 > qw) {
; #pragma unroll
;                 for (int kb = 0; kb < 4; ++kb)
; #pragma unroll
;                     for (int qq = 0; qq < 2; ++qq)
; #pragma unroll
;                         for (int j = 0; j < 4; ++j) if (kt * 64 + kb * 16 + quad * 4 + j > qw + qq * 16 + l15) st[kb][qq][j] = -INFINITY; }
;     ...
;         if (more) { *(LAS u32x4*)(bufn + AT_K + skey * 144 + sch * 16) = kreg; *(LAS u32x4*)(bufn + AT_V + skey * 160 + sch * 16) = vreg; if (tid < 64) ((LAS float*)(bufn + AT_CK))[tid] = ckreg; }
.LBB0_278:
	s_waitcnt vmcnt(1)
	ds_write_b128 v217, v[34:37]
	s_waitcnt vmcnt(0)
	ds_write_b128 v218, v[38:41] offset:9216
	s_and_saveexec_b64 s[14:15], s[40:41]
	v_mul_f32_e32 v180, 0x3fb8aa3b, v180
	ds_write_b32 v216, v180 offset:19456
	s_or_b64 exec, exec, s[14:15]
	s_andn2_b64 vcc, exec, s[16:17]
	s_waitcnt lgkmcnt(0)
	s_barrier
	s_cbranch_vccnz .LBB0_236
	v_readlane_b32 s12, v253, 61
	s_andn2_b64 vcc, exec, s[42:43]
	s_nop 0
	v_add_u32_e32 v90, s12, v111
	ds_read_b128 v[34:37], v90 offset:19456
	ds_read_b128 v[38:41], v219
	ds_read_b128 v[66:69], v219 offset:64
	ds_read_b128 v[78:81], v90 offset:19520
	ds_read_b128 v[82:85], v219 offset:2304
	s_waitcnt lgkmcnt(4)
	v_sub_f32_e32 v73, v25, v37
	v_sub_f32_e32 v72, v24, v36
	v_sub_f32_e32 v71, v23, v35
	v_sub_f32_e32 v70, v20, v34
	v_sub_f32_e32 v37, v21, v37
	v_sub_f32_e32 v36, v22, v36
	v_sub_f32_e32 v35, v19, v35
	v_sub_f32_e32 v34, v18, v34
	s_waitcnt lgkmcnt(3)
	v_mfma_f32_16x16x32_bf16 v[70:73], v[38:41], v[6:9], v[70:73]
	v_mfma_f32_16x16x32_bf16 v[34:37], v[38:41], v[14:17], v[34:37]
	s_waitcnt lgkmcnt(2)
	v_mfma_f32_16x16x32_bf16 v[38:41], v[66:69], v[10:13], v[34:37]
	v_mfma_f32_16x16x32_bf16 v[70:73], v[66:69], v[2:5], v[70:73]
	s_nop 4
	ds_read_b128 v[34:37], v219 offset:2368
	s_waitcnt lgkmcnt(2)
	v_sub_f32_e32 v69, v25, v81
	v_sub_f32_e32 v68, v24, v80
	v_sub_f32_e32 v67, v23, v79
	v_sub_f32_e32 v66, v20, v78
	s_waitcnt lgkmcnt(1)
	s_nop 0
	v_mfma_f32_16x16x32_bf16 v[66:69], v[82:85], v[6:9], v[66:69]
	s_waitcnt lgkmcnt(0)
	v_mfma_f32_16x16x32_bf16 v[74:77], v[34:37], v[2:5], v[66:69]
	s_nop 5
	v_sub_f32_e32 v69, v21, v81
	v_sub_f32_e32 v68, v22, v80
	v_sub_f32_e32 v67, v19, v79
	v_sub_f32_e32 v66, v18, v78
	s_nop 1
	v_mfma_f32_16x16x32_bf16 v[66:69], v[82:85], v[14:17], v[66:69]
	ds_read_b128 v[82:85], v219 offset:4608
	ds_read_b128 v[86:89], v90 offset:19584
	s_waitcnt lgkmcnt(0)
	v_sub_f32_e32 v81, v25, v89
	v_sub_f32_e32 v80, v24, v88
	v_sub_f32_e32 v79, v23, v87
	v_sub_f32_e32 v78, v20, v86
	v_sub_f32_e32 v89, v21, v89
	v_sub_f32_e32 v88, v22, v88
	v_sub_f32_e32 v87, v19, v87
	v_sub_f32_e32 v86, v18, v86
	v_mfma_f32_16x16x32_bf16 v[34:37], v[34:37], v[10:13], v[66:69]
	s_nop 2
	ds_read_b128 v[66:69], v219 offset:4672
	ds_read_b128 v[90:93], v90 offset:19648
	s_waitcnt lgkmcnt(0)
	v_sub_f32_e32 v97, v25, v93
	v_mfma_f32_16x16x32_bf16 v[78:81], v[82:85], v[6:9], v[78:81]
	v_sub_f32_e32 v96, v24, v92
	v_sub_f32_e32 v95, v23, v91
	v_sub_f32_e32 v94, v20, v90
	v_mfma_f32_16x16x32_bf16 v[82:85], v[82:85], v[14:17], v[86:89]
	s_nop 2
	ds_read_b128 v[86:89], v220
	v_mfma_f32_16x16x32_bf16 v[78:81], v[66:69], v[2:5], v[78:81]
	v_mfma_f32_16x16x32_bf16 v[66:69], v[66:69], v[10:13], v[82:85]
	s_nop 2
	ds_read_b128 v[82:85], v220 offset:64
	s_waitcnt lgkmcnt(1)
	v_mfma_f32_16x16x32_bf16 v[6:9], v[86:89], v[6:9], v[94:97]
	s_waitcnt lgkmcnt(0)
	v_mfma_f32_16x16x32_bf16 v[2:5], v[82:85], v[2:5], v[6:9]
	s_nop 5
	v_sub_f32_e32 v9, v21, v93
	v_sub_f32_e32 v8, v22, v92
	v_sub_f32_e32 v7, v19, v91
	v_sub_f32_e32 v6, v18, v90
	s_nop 1
	v_mfma_f32_16x16x32_bf16 v[6:9], v[86:89], v[14:17], v[6:9]
	v_mfma_f32_16x16x32_bf16 v[10:13], v[82:85], v[10:13], v[6:9]
	s_cbranch_vccnz .LBB0_235
	v_readlane_b32 s14, v254, 57
	v_readlane_b32 s15, v254, 58
	s_nop 3
	v_mov_b32_e32 v6, s31
	v_cndmask_b32_e64 v6, v70, v6, s[44:45]
	v_cndmask_b32_e64 v72, v72, v199, s[14:15]
	v_readlane_b32 s14, v254, 59
	v_readlane_b32 s15, v254, 60
	v_cndmask_b32_e64 v70, v6, v70, s[46:47]
	v_mov_b32_e32 v6, s31
	v_cndmask_b32_e64 v73, v73, v199, s[14:15]
	v_readlane_b32 s14, v254, 61
	v_readlane_b32 s15, v254, 62
	v_cndmask_b32_e64 v71, v199, v71, s[46:47]
	v_cndmask_b32_e64 v39, v199, v39, s[54:55]
	v_cndmask_b32_e64 v6, v38, v6, s[14:15]
	v_readlane_b32 s14, v254, 63
	v_readlane_b32 s15, v252, 0
	v_cndmask_b32_e64 v38, v6, v38, s[54:55]
	v_mov_b32_e32 v6, s31
	v_cndmask_b32_e64 v40, v40, v199, s[14:15]
	v_readlane_b32 s14, v252, 1
	v_readlane_b32 s15, v252, 2
	v_cndmask_b32_e64 v34, v34, v6, s[44:45]
	v_cndmask_b32_e64 v35, v35, v199, s[68:69]
	v_cndmask_b32_e64 v41, v41, v199, s[14:15]
	v_readlane_b32 s14, v252, 3
	v_readlane_b32 s15, v252, 4
	v_cndmask_b32_e64 v36, v36, v199, s[70:71]
	v_cndmask_b32_e64 v37, v37, v199, s[72:73]
	v_cndmask_b32_e64 v74, v74, v6, s[14:15]
	v_readlane_b32 s14, v252, 5
	v_readlane_b32 s15, v252, 6
	v_cndmask_b32_e64 v78, v78, v6, s[74:75]
	v_cndmask_b32_e64 v79, v79, v199, s[76:77]
	v_cndmask_b32_e64 v75, v75, v199, s[14:15]
	v_readlane_b32 s14, v252, 7
	v_readlane_b32 s15, v252, 8
	v_cndmask_b32_e64 v80, v80, v199, s[78:79]
	v_cndmask_b32_e64 v81, v81, v199, s[80:81]
	v_cndmask_b32_e64 v76, v76, v199, s[14:15]
	v_readlane_b32 s14, v252, 9
	v_readlane_b32 s15, v252, 10
	v_cndmask_b32_e64 v66, v66, v6, s[82:83]
	v_cndmask_b32_e64 v67, v67, v199, s[84:85]
	v_cndmask_b32_e64 v77, v77, v199, s[14:15]
	v_cndmask_b32_e64 v68, v68, v199, s[86:87]
	v_cndmask_b32_e64 v69, v69, v199, s[88:89]
	v_cndmask_b32_e64 v2, v2, v6, s[90:91]
	v_cndmask_b32_e64 v3, v3, v199, s[92:93]
	v_cndmask_b32_e64 v4, v4, v199, s[94:95]
	v_cndmask_b32_e64 v5, v5, v199, s[96:97]
	v_cndmask_b32_e64 v10, v10, v6, s[4:5]
	v_cndmask_b32_e64 v11, v11, v199, s[6:7]
	v_cndmask_b32_e64 v12, v12, v199, s[8:9]
	v_cndmask_b32_e64 v13, v13, v199, s[10:11]
	s_branch .LBB0_235

; __device__ __forceinline__ void phase_prep(ArgsK& a, int gw, int NGW, int lane) {
;     ...
;     for (int sq = gw; sq < 512; sq += NGW) {
;         const bool smp = sq >= 256; const int bh = sq & 255, b = bh >> 3, h = bh & 7;
;         const float* src = smp ? a.in[4] + ((size_t)b * PASTL) * 8 + h : a.out + O_FLP + ((size_t)b * SEQ) * 8 + h;
;         float* dst = smp ? (float*)(a.ws + WS_CUMS) + ((size_t)b * CTOT) * 8 + h : (float*)(a.ws + WS_CUMP) + ((size_t)b * SEQ) * 8 + h;
;         float tot = 0.f;
;         for (int i = 0; i < 32; ++i) tot += src[(size_t)(lane * 32 + i) * 8];
;         float inc = tot;
; #pragma unroll
;         for (int o = 1; o < 64; o <<= 1) { const float nb = __shfl_up(inc, o); if (lane >= o) inc += nb; }
;         float run = inc - tot;
;         for (int i = 0; i < 32; ++i) { run += src[(size_t)(lane * 32 + i) * 8]; dst[(size_t)(lane * 32 + i) * 8] = run; }
.LBB0_459:
	s_bfe_u32 s25, s24, 0x50003
	s_lshl_b32 s14, s25, 14
	s_lshl_b32 s15, s25, 16
	s_cmpk_gt_i32 s24, 0xff
	s_mul_i32 s28, s25, 0x4080
	s_cselect_b32 s17, s0, s12
	s_cselect_b32 s14, s28, s14
	s_mov_b32 s28, 0x5500000
	s_cselect_b32 s16, s1, s18
	s_cselect_b32 s28, s28, 0x5300000
	s_add_u32 s15, s17, s15
	s_addc_u32 s17, s16, 0
	s_add_u32 s16, s15, s19
	s_addc_u32 s17, s17, 0
	global_load_dword v48, v8, s[16:17]
	global_load_dword v49, v8, s[16:17] offset:32
	global_load_dword v50, v8, s[16:17] offset:64
	global_load_dword v51, v8, s[16:17] offset:96
	global_load_dword v52, v8, s[16:17] offset:128
	global_load_dword v53, v8, s[16:17] offset:160
	global_load_dword v54, v8, s[16:17] offset:192
	global_load_dword v55, v8, s[16:17] offset:224
	global_load_dword v56, v8, s[16:17] offset:256
	global_load_dword v57, v8, s[16:17] offset:288
	global_load_dword v58, v8, s[16:17] offset:320
	global_load_dword v59, v8, s[16:17] offset:352
	global_load_dword v60, v8, s[16:17] offset:384
	global_load_dword v61, v8, s[16:17] offset:416
	global_load_dword v62, v8, s[16:17] offset:448
	global_load_dword v63, v8, s[16:17] offset:480
	global_load_dword v64, v8, s[16:17] offset:512
	global_load_dword v65, v8, s[16:17] offset:544
	global_load_dword v66, v8, s[16:17] offset:576
	global_load_dword v67, v8, s[16:17] offset:608
	global_load_dword v68, v8, s[16:17] offset:640
	global_load_dword v69, v8, s[16:17] offset:672
	global_load_dword v70, v8, s[16:17] offset:704
	global_load_dword v71, v8, s[16:17] offset:736
	global_load_dword v72, v8, s[16:17] offset:768
	global_load_dword v73, v8, s[16:17] offset:800
	global_load_dword v74, v8, s[16:17] offset:832
	global_load_dword v75, v8, s[16:17] offset:864
	global_load_dword v76, v8, s[16:17] offset:896
	global_load_dword v77, v8, s[16:17] offset:928
	global_load_dword v78, v8, s[16:17] offset:960
	global_load_dword v79, v8, s[16:17] offset:992
	s_load_dwordx2 s[34:35], s[38:39], 0xf8
	s_waitcnt lgkmcnt(0)
	s_add_u32 s15, s34, s28
	s_addc_u32 s28, s35, 0
	s_lshl_b32 s14, s14, 2
	s_add_u32 s14, s15, s14
	s_addc_u32 s15, s28, 0
	s_add_u32 s14, s14, s19
	s_addc_u32 s15, s15, 0
	s_cmpk_lt_i32 s24, 0x100
	s_waitcnt vmcnt(0)
	v_add_f32_e32 v9, 0, v48
	v_add_f32_e32 v9, v9, v49
	v_add_f32_e32 v9, v9, v50
	v_add_f32_e32 v9, v9, v51
	v_add_f32_e32 v9, v9, v52
	v_add_f32_e32 v9, v9, v53
	v_add_f32_e32 v9, v9, v54
	v_add_f32_e32 v9, v9, v55
	v_add_f32_e32 v9, v9, v56
	v_add_f32_e32 v9, v9, v57
	v_add_f32_e32 v9, v9, v58
	v_add_f32_e32 v9, v9, v59
	v_add_f32_e32 v9, v9, v60
	v_add_f32_e32 v9, v9, v61
	v_add_f32_e32 v9, v9, v62
	v_add_f32_e32 v9, v9, v63
	v_add_f32_e32 v9, v9, v64
	v_add_f32_e32 v9, v9, v65
	v_add_f32_e32 v9, v9, v66
	v_add_f32_e32 v9, v9, v67
	v_add_f32_e32 v9, v9, v68
	v_add_f32_e32 v9, v9, v69
	v_add_f32_e32 v9, v9, v70
	v_add_f32_e32 v9, v9, v71
	v_add_f32_e32 v9, v9, v72
	v_add_f32_e32 v9, v9, v73
	v_add_f32_e32 v9, v9, v74
	v_add_f32_e32 v9, v9, v75
	v_add_f32_e32 v9, v9, v76
	v_add_f32_e32 v9, v9, v77
	v_add_f32_e32 v9, v9, v78
	v_add_f32_e32 v11, v9, v79
	ds_bpermute_b32 v9, v0, v11
	s_waitcnt lgkmcnt(0)
	v_add_f32_e32 v9, v11, v9
	v_cndmask_b32_e32 v9, v9, v11, vcc
	ds_bpermute_b32 v12, v2, v9
	s_waitcnt lgkmcnt(0)
	v_add_f32_e32 v12, v9, v12
	v_cndmask_b32_e64 v9, v12, v9, s[4:5]
	ds_bpermute_b32 v12, v3, v9
	s_waitcnt lgkmcnt(0)
	v_add_f32_e32 v12, v9, v12
	v_cndmask_b32_e64 v9, v12, v9, s[6:7]
	ds_bpermute_b32 v12, v4, v9
	s_waitcnt lgkmcnt(0)
	v_add_f32_e32 v12, v9, v12
	v_cndmask_b32_e64 v9, v12, v9, s[8:9]
	ds_bpermute_b32 v12, v5, v9
	s_waitcnt lgkmcnt(0)
	v_add_f32_e32 v12, v9, v12
	v_cndmask_b32_e64 v9, v12, v9, s[10:11]
	ds_bpermute_b32 v12, v6, v9
	s_waitcnt lgkmcnt(0)
	v_add_f32_e32 v12, v9, v12
	v_cndmask_b32_e64 v9, v12, v9, s[40:41]
	v_sub_f32_e32 v11, v9, v11
	v_add_f32_e32 v10, v48, v11
	global_store_dword v8, v10, s[14:15]
	v_add_f32_e32 v10, v10, v49
	global_store_dword v8, v10, s[14:15] offset:32
	v_add_f32_e32 v10, v10, v50
	global_store_dword v8, v10, s[14:15] offset:64
	v_add_f32_e32 v10, v10, v51
	global_store_dword v8, v10, s[14:15] offset:96
	v_add_f32_e32 v10, v10, v52
	global_store_dword v8, v10, s[14:15] offset:128
	v_add_f32_e32 v10, v10, v53
	global_store_dword v8, v10, s[14:15] offset:160
	v_add_f32_e32 v10, v10, v54
	global_store_dword v8, v10, s[14:15] offset:192
	v_add_f32_e32 v10, v10, v55
	global_store_dword v8, v10, s[14:15] offset:224
	v_add_f32_e32 v10, v10, v56
	global_store_dword v8, v10, s[14:15] offset:256
	v_add_f32_e32 v10, v10, v57
	global_store_dword v8, v10, s[14:15] offset:288
	v_add_f32_e32 v10, v10, v58
	global_store_dword v8, v10, s[14:15] offset:320
	v_add_f32_e32 v10, v10, v59
	global_store_dword v8, v10, s[14:15] offset:352
	v_add_f32_e32 v10, v10, v60
	global_store_dword v8, v10, s[14:15] offset:384
	v_add_f32_e32 v10, v10, v61
	global_store_dword v8, v10, s[14:15] offset:416
	v_add_f32_e32 v10, v10, v62
	global_store_dword v8, v10, s[14:15] offset:448
	v_add_f32_e32 v10, v10, v63
	global_store_dword v8, v10, s[14:15] offset:480
	v_add_f32_e32 v10, v10, v64
	global_store_dword v8, v10, s[14:15] offset:512
	v_add_f32_e32 v10, v10, v65
	global_store_dword v8, v10, s[14:15] offset:544
	v_add_f32_e32 v10, v10, v66
	global_store_dword v8, v10, s[14:15] offset:576
	v_add_f32_e32 v10, v10, v67
	global_store_dword v8, v10, s[14:15] offset:608
	v_add_f32_e32 v10, v10, v68
	global_store_dword v8, v10, s[14:15] offset:640
	v_add_f32_e32 v10, v10, v69
	global_store_dword v8, v10, s[14:15] offset:672
	v_add_f32_e32 v10, v10, v70
	global_store_dword v8, v10, s[14:15] offset:704
	v_add_f32_e32 v10, v10, v71
	global_store_dword v8, v10, s[14:15] offset:736
	v_add_f32_e32 v10, v10, v72
	global_store_dword v8, v10, s[14:15] offset:768
	v_add_f32_e32 v10, v10, v73
	global_store_dword v8, v10, s[14:15] offset:800
	v_add_f32_e32 v10, v10, v74
	global_store_dword v8, v10, s[14:15] offset:832
	v_add_f32_e32 v10, v10, v75
	global_store_dword v8, v10, s[14:15] offset:864
	v_add_f32_e32 v10, v10, v76
	global_store_dword v8, v10, s[14:15] offset:896
	v_add_f32_e32 v10, v10, v77
	global_store_dword v8, v10, s[14:15] offset:928
	v_add_f32_e32 v10, v10, v78
	global_store_dword v8, v10, s[14:15] offset:960
	v_add_f32_e32 v10, v10, v79
	global_store_dword v8, v10, s[14:15] offset:992
	s_cbranch_scc1 .LBB0_458
; __device__ __forceinline__ void phase_prep(ArgsK& a, int gw, int NGW, int lane) {
;     ...
;         if (smp) { float endv = __shfl(inc, 63);
;             if (lane == 0) { const float* nsrc = a.out + O_FLS + ((size_t)b * DSEQ) * 8 + h;
;                 for (int i = 0; i < DSEQ; ++i) { endv += nsrc[i * 8]; dst[(size_t)(PASTL + i) * 8] = endv; } } }
	ds_bpermute_b32 v9, v7, v9
	s_and_saveexec_b64 s[16:17], vcc
	s_cbranch_execz .LBB0_457
	s_lshl_b32 s25, s25, 9
	v_mov_b32_e32 v10, s25
	global_load_dword v80, v10, s[2:3]
	global_load_dword v81, v10, s[2:3] offset:32
	global_load_dword v82, v10, s[2:3] offset:64
	global_load_dword v83, v10, s[2:3] offset:96
	global_load_dword v84, v10, s[2:3] offset:128
	global_load_dword v85, v10, s[2:3] offset:160
	global_load_dword v86, v10, s[2:3] offset:192
	global_load_dword v87, v10, s[2:3] offset:224
	global_load_dword v88, v10, s[2:3] offset:256
	global_load_dword v89, v10, s[2:3] offset:288
	global_load_dword v90, v10, s[2:3] offset:320
	global_load_dword v91, v10, s[2:3] offset:352
	global_load_dword v92, v10, s[2:3] offset:384
	global_load_dword v93, v10, s[2:3] offset:416
	global_load_dword v94, v10, s[2:3] offset:448
	global_load_dword v95, v10, s[2:3] offset:480
	s_waitcnt vmcnt(0) lgkmcnt(0)
	v_add_f32_e32 v9, v80, v9
	global_store_dword v196, v9, s[14:15]
	v_add_f32_e32 v9, v9, v81
	global_store_dword v196, v9, s[14:15] offset:32
	v_add_f32_e32 v9, v9, v82
	global_store_dword v196, v9, s[14:15] offset:64
	v_add_f32_e32 v9, v9, v83
	global_store_dword v196, v9, s[14:15] offset:96
	v_add_f32_e32 v9, v9, v84
	global_store_dword v196, v9, s[14:15] offset:128
	v_add_f32_e32 v9, v9, v85
	global_store_dword v196, v9, s[14:15] offset:160
	v_add_f32_e32 v9, v9, v86
	global_store_dword v196, v9, s[14:15] offset:192
	v_add_f32_e32 v9, v9, v87
	global_store_dword v196, v9, s[14:15] offset:224
	v_add_f32_e32 v9, v9, v88
	global_store_dword v196, v9, s[14:15] offset:256
	v_add_f32_e32 v9, v9, v89
	global_store_dword v196, v9, s[14:15] offset:288
	v_add_f32_e32 v9, v9, v90
	global_store_dword v196, v9, s[14:15] offset:320
	v_add_f32_e32 v9, v9, v91
	global_store_dword v196, v9, s[14:15] offset:352
	v_add_f32_e32 v9, v9, v92
	global_store_dword v196, v9, s[14:15] offset:384
	v_add_f32_e32 v9, v9, v93
	global_store_dword v196, v9, s[14:15] offset:416
	v_add_f32_e32 v9, v9, v94
	global_store_dword v196, v9, s[14:15] offset:448
	v_add_f32_e32 v9, v9, v95
	global_store_dword v196, v9, s[14:15] offset:480
	s_branch .LBB0_457
